# attention tile-loop barrier edges: rare-path test ahead of the tile barrier (own barrier copy in the rare blocks), even-head flag computed in the first QK MFMA shadow
# baseline (speedup 1.0000x reference)
.Ltb_u1_b:
	s_ashr_i32 s11, s6, 6
	s_lshl_b32 s10, s43, 4
	s_lshl_b32 s26, s11, 2
	v_bfe_u32 v233, v237, 4, 2
	s_and_b32 s60, s10, 0xfffff000
	v_or_b32_e32 v52, s26, v233
	s_waitcnt vmcnt(0)
	v_add_u32_e32 v2, s60, v52
	v_ashrrev_i32_e32 v3, 31, v2
	v_readlane_b32 s18, v252, 31
	v_bitop3_b32 v0, s26, v237, v233 bitop3:0x36
	v_lshlrev_b64 v[2:3], 12, v[2:3]
	v_readlane_b32 s19, v252, 32
	s_and_b32 s46, s43, 15
	s_lshl_b32 s84, s28, 8
	v_lshl_add_u64 v[2:3], s[18:19], 0, v[2:3]
	v_lshlrev_b32_e32 v0, 4, v0
	s_xor_b32 s17, s46, 31
	s_and_b32 s2, s11, 3
	v_lshl_add_u64 v[2:3], v[2:3], 0, s[84:85]
	v_and_b32_e32 v0, 0xf0, v0
	s_lshl_b32 s27, s11, 3
	v_bfe_u32 v53, v237, 3, 3
	s_lshl_b32 s21, s17, 7
	s_lshl_b32 s22, s2, 5
	s_lshl_b32 s18, s28, 7
	v_lshl_add_u64 v[2:3], v[2:3], 0, v[0:1]
	v_or_b32_e32 v0, s27, v53
	s_or_b32 s20, s22, s21
	v_lshrrev_b32_e32 v54, 1, v0
	v_add_u32_e32 v4, s18, v0
	v_and_b32_e32 v235, 31, v237
	v_xor_b32_e32 v6, v54, v237
	v_ashrrev_i32_e32 v5, 31, v4
	v_readlane_b32 s36, v252, 39
	s_or_b32 s10, s20, s60
	v_lshlrev_b64 v[4:5], 15, v[4:5]
	v_readlane_b32 s37, v252, 40
	v_lshlrev_b32_e32 v0, 4, v6
	v_or_b32_e32 v6, s10, v235
	v_lshl_add_u64 v[4:5], s[36:37], 0, v[4:5]
	v_ashrrev_i32_e32 v7, 31, v6
	v_readlane_b32 s36, v252, 17
	s_ashr_i32 s3, s6, 8
	v_lshlrev_b64 v[6:7], 12, v[6:7]
	v_readlane_b32 s37, v252, 18
	s_ashr_i32 s61, s60, 31
	v_bfe_u32 v234, v237, 5, 1
	v_lshl_add_u64 v[6:7], s[36:37], 0, v[6:7]
	s_lshl_b32 s36, s3, 6
	v_lshl_add_u64 v[4:5], s[60:61], 1, v[4:5]
	v_and_b32_e32 v0, 0x70, v0
	v_lshl_add_u64 v[6:7], v[6:7], 0, s[84:85]
	s_ashr_i32 s37, s36, 31
	v_lshl_add_u64 v[4:5], v[4:5], 0, v[0:1]
	v_lshl_add_u64 v[6:7], s[36:37], 1, v[6:7]
	v_lshlrev_b32_e32 v0, 4, v234
	v_lshl_add_u64 v[6:7], v[6:7], 0, v[0:1]
	global_load_dwordx4 v[146:149], v[6:7], off nt
	global_load_dwordx4 v[150:153], v[6:7], off offset:32 nt
	global_load_dwordx4 v[154:157], v[6:7], off offset:64 nt
	global_load_dwordx4 v[158:161], v[6:7], off offset:96 nt
	s_lshl_b32 s11, s11, 10
	s_add_i32 s11, s11, 0
	s_mov_b32 m0, s11
	s_mov_b64 s[36:37], 0x20000
	global_load_lds_dwordx4 v[2:3], off
	v_lshl_add_u64 v[8:9], v[2:3], 0, s[36:37]
	s_add_i32 m0, s11, 0x2000
	s_mov_b64 s[36:37], 0x40000
	global_load_lds_dwordx4 v[8:9], off
	s_add_i32 m0, s11, 0x4000
	v_lshl_add_u64 v[8:9], v[2:3], 0, s[36:37]
	s_mov_b64 s[36:37], 0x60000
	global_load_lds_dwordx4 v[8:9], off
	v_lshl_add_u64 v[8:9], v[2:3], 0, s[36:37]
	s_add_i32 m0, s11, 0x6000
	s_mov_b64 s[36:37], 0x200000
	global_load_lds_dwordx4 v[8:9], off
	s_add_i32 m0, s11, 0xc000
	v_lshl_add_u64 v[8:9], v[4:5], 0, s[36:37]
	global_load_lds_dwordx4 v[4:5], off
	s_add_i32 m0, s11, 0xe000
	s_mov_b64 s[36:37], 0xa0000
	global_load_lds_dwordx4 v[8:9], off
	s_add_i32 m0, s11, 0x8000
	v_lshl_add_u64 v[8:9], v[2:3], 0, s[34:35]
	global_load_lds_dwordx4 v[8:9], off
	v_lshl_add_u64 v[2:3], v[2:3], 0, s[36:37]
	s_add_i32 m0, s11, 0xa000
	s_mov_b64 s[36:37], 0x80
	global_load_lds_dwordx4 v[2:3], off
	s_add_i32 m0, s11, 0x10000
	v_lshl_add_u64 v[2:3], v[4:5], 0, s[36:37]
	s_mov_b64 s[36:37], 0x200080
	global_load_lds_dwordx4 v[2:3], off
	v_lshl_add_u64 v[2:3], v[4:5], 0, s[36:37]
	s_add_i32 m0, s11, 0x12000
	v_and_b32_e32 v0, 19, v237
	global_load_lds_dwordx4 v[2:3], off
	v_lshlrev_b32_e32 v2, 1, v237
	v_lshrrev_b32_e32 v35, 1, v34
	v_and_or_b32 v0, v2, 8, v0
	v_and_b32_e32 v22, 4, v35
	v_or_b32_e32 v2, v0, v22
	v_lshl_or_b32 v45, s3, 3, v234
	v_lshlrev_b32_e32 v44, 8, v2
	v_bitop3_b32 v2, v2, v45, 15 bitop3:0x6c
	v_lshl_add_u32 v239, v2, 4, v44
	s_waitcnt vmcnt(4)
	s_barrier
	v_add_u32_e32 v6, 0, v239
	v_bitop3_b32 v0, v0, 15, v22 bitop3:0xc8
	ds_read_b128 v[2:5], v6
	ds_read_b128 v[18:21], v6 offset:8192
	v_bitop3_b32 v22, v45, v0, 2 bitop3:0x36
	v_lshl_add_u32 v240, v22, 4, v44
	v_add_u32_e32 v40, 0, v240
	ds_read_b128 v[36:39], v40
	s_waitcnt vmcnt(0) lgkmcnt(0)
	v_mfma_f32_32x32x16_bf16 v[2:17], v[2:5], v[146:149], 0
	ds_read_b128 v[40:43], v40 offset:8192
	v_bfe_u32 v34, v34, 1, 3
	v_bitop3_b32 v57, v234, v34, 2 bitop3:0x36
	v_bitop3_b32 v58, v234, v34, 4 bitop3:0x36
	v_bitop3_b32 v59, v234, v34, 6 bitop3:0x36
	s_and_b32 s56, s42, 0xfffff000
	s_add_i32 s26, s26, s56
	v_mfma_f32_32x32x16_bf16 v[18:33], v[18:21], v[146:149], 0
	s_lshr_b32 s16, s43, 4
	s_and_b32 s16, s16, 15
	s_lshl_b32 s36, s16, 7
	s_lshl_b32 s37, s16, 8
	s_add_i32 s27, s27, s36
	s_ashr_i32 s57, s56, 31
	s_lshl_b64 s[44:45], s[56:57], 1
	v_mfma_f32_32x32x16_bf16 v[2:17], v[36:39], v[150:153], v[2:17]
	v_bitop3_b32 v36, v45, v0, 4 bitop3:0x36
	v_lshl_add_u32 v241, v36, 4, v44
	v_add_u32_e32 v46, 0, v241
	ds_read_b128 v[36:39], v46
	v_bitop3_b32 v0, v45, v0, 6 bitop3:0x36
	v_lshl_add_u32 v243, v0, 4, v44
	v_add_u32_e32 v0, 0, v243
	s_waitcnt lgkmcnt(1)
	v_mfma_f32_32x32x16_bf16 v[18:33], v[40:43], v[150:153], v[18:33]
	ds_read_b128 v[40:43], v46 offset:8192
	v_lshlrev_b32_e32 v236, 3, v234
	s_mov_b32 s84, s85
	v_bitop3_b32 v56, v35, v234, 7 bitop3:0x6c
	s_mov_b32 s86, s85
	s_mov_b32 s87, s85
	s_mov_b32 s88, s85
	s_waitcnt lgkmcnt(1)
	v_mfma_f32_32x32x16_bf16 v[2:17], v[36:39], v[154:157], v[2:17]
	ds_read_b128 v[36:39], v0
	s_mov_b32 s89, s85
	s_mov_b32 s90, s85
	s_mov_b32 s91, s85
	s_mov_b32 s92, s85
	s_mov_b32 s93, s85
	s_mov_b32 s94, s85
	s_waitcnt lgkmcnt(1)
	v_mfma_f32_32x32x16_bf16 v[18:33], v[40:43], v[154:157], v[18:33]
	ds_read_b128 v[40:43], v0 offset:8192
	s_mov_b32 s95, s85
	s_mov_b32 s96, s85
	s_mov_b32 s97, s85
	s_mov_b32 s98, s85
	s_mov_b32 s99, s85
	s_lshl_b32 s16, s17, 1
	s_waitcnt lgkmcnt(1)
	v_mfma_f32_32x32x16_bf16 v[2:17], v[36:39], v[158:161], v[2:17]
	v_lshlrev_b32_e32 v55, 7, v235
	s_lshr_b32 s19, s20, 6
	s_add_i32 s17, s16, 2
	s_add_i32 s19, s19, 1
	v_lshl_or_b32 v244, v56, 4, v55
	v_lshl_or_b32 v245, v57, 4, v55
	v_lshl_or_b32 v246, v58, 4, v55
	s_waitcnt lgkmcnt(0)
	v_mfma_f32_32x32x16_bf16 v[18:33], v[40:43], v[158:161], v[18:33]
	s_nop 2
	v_max_f32_e32 v34, v3, v3
	v_lshl_or_b32 v247, v59, 4, v55
	s_mov_b32 s23, 1
	v_and_b32_e32 v238, 63, v237
	s_mov_b32 s31, 0x8000
	s_min_u32 s19, s17, s19
	s_addk_i32 s20, 0xff50
	s_nop 1
	v_max_f32_e32 v0, v19, v19
	v_max_f32_e32 v0, v34, v0
	v_max3_f32 v0, v2, v18, v0
	v_max3_f32 v34, v20, v5, v21
	v_max3_f32 v0, v0, v4, v34
	v_max3_f32 v34, v22, v7, v23
	v_max3_f32 v0, v0, v6, v34
	v_max3_f32 v34, v24, v9, v25
	v_max3_f32 v0, v0, v8, v34
	v_max3_f32 v34, v26, v11, v27
	v_max3_f32 v0, v0, v10, v34
	v_max3_f32 v34, v28, v13, v29
	v_max3_f32 v0, v0, v12, v34
	v_max3_f32 v34, v30, v15, v31
	v_max3_f32 v0, v0, v14, v34
	v_max3_f32 v34, v32, v17, v33
	v_max3_f32 v0, v0, v16, v34
	v_mov_b32_e32 v34, v0
	s_nop 1
	v_permlane32_swap_b32_e32 v0, v34
	v_max_f32_e32 v34, v34, v34
	v_max_f32_e32 v0, v0, v0
	v_max_f32_e32 v213, v0, v34
	v_sub_f32_e32 v0, v2, v213
	v_exp_f32_e32 v60, v0
	v_sub_f32_e32 v0, v18, v213
	v_exp_f32_e32 v61, v0
	v_sub_f32_e32 v0, v3, v213
	v_sub_f32_e32 v2, v19, v213
	v_exp_f32_e32 v0, v0
	v_exp_f32_e32 v2, v2
	v_add_f32_e32 v3, v61, v60
	v_mov_b64_e32 v[34:35], s[84:85]
	v_cvt_pk_bf16_f32 v162, v60, v0
	v_pk_add_f32 v[18:19], v[2:3], v[0:1]
	v_sub_f32_e32 v3, v4, v213
	v_sub_f32_e32 v4, v20, v213
	v_pk_add_f32 v[18:19], v[18:19], v[18:19] op_sel_hi:[0,1]
	v_exp_f32_e32 v62, v4
	v_sub_f32_e32 v4, v5, v213
	v_exp_f32_e32 v3, v3
	v_exp_f32_e32 v18, v4
	v_sub_f32_e32 v4, v21, v213
	v_exp_f32_e32 v4, v4
	v_add_f32_e32 v5, v62, v3
	v_sub_u32_e32 v0, 7, v237
	v_cvt_pk_bf16_f32 v178, v61, v2
	v_pk_add_f32 v[20:21], v[4:5], v[18:19]
	v_sub_f32_e32 v5, v6, v213
	v_sub_f32_e32 v6, v22, v213
	v_pk_add_f32 v[20:21], v[20:21], v[20:21] op_sel_hi:[0,1]
	v_exp_f32_e32 v19, v6
	v_sub_f32_e32 v6, v7, v213
	v_exp_f32_e32 v5, v5
	v_exp_f32_e32 v20, v6
	v_sub_f32_e32 v6, v23, v213
	v_exp_f32_e32 v6, v6
	v_add_f32_e32 v7, v19, v5
	v_and_b32_e32 v0, 3, v0
	v_mov_b32_e32 v2, s33
	v_pk_add_f32 v[22:23], v[6:7], v[20:21]
	v_sub_f32_e32 v7, v8, v213
	v_sub_f32_e32 v8, v24, v213
	v_pk_add_f32 v[22:23], v[22:23], v[22:23] op_sel_hi:[0,1]
	v_exp_f32_e32 v21, v8
	v_sub_f32_e32 v8, v9, v213
	v_exp_f32_e32 v7, v7
	v_exp_f32_e32 v22, v8
	v_sub_f32_e32 v8, v25, v213
	v_exp_f32_e32 v8, v8
	v_add_f32_e32 v9, v21, v7
	s_movk_i32 s33, 0x510
	v_mad_u32_u24 v0, v0, s33, v2
	v_pk_add_f32 v[24:25], v[8:9], v[22:23]
	v_sub_f32_e32 v9, v10, v213
	v_sub_f32_e32 v10, v26, v213
	v_pk_add_f32 v[24:25], v[24:25], v[24:25] op_sel_hi:[0,1]
	v_exp_f32_e32 v23, v10
	v_sub_f32_e32 v10, v11, v213
	v_exp_f32_e32 v9, v9
	v_exp_f32_e32 v24, v10
	v_sub_f32_e32 v10, v27, v213
	v_exp_f32_e32 v10, v10
	v_add_f32_e32 v11, v23, v9
	v_or_b32_e32 v2, s26, v233
	v_cvt_pk_bf16_f32 v163, v3, v18
	v_pk_add_f32 v[26:27], v[10:11], v[24:25]
	v_sub_f32_e32 v11, v12, v213
	v_sub_f32_e32 v12, v28, v213
	v_pk_add_f32 v[26:27], v[26:27], v[26:27] op_sel_hi:[0,1]
	v_exp_f32_e32 v25, v12
	v_sub_f32_e32 v12, v13, v213
	v_exp_f32_e32 v11, v11
	v_exp_f32_e32 v26, v12
	v_sub_f32_e32 v12, v29, v213
	v_exp_f32_e32 v12, v12
	v_add_f32_e32 v13, v25, v11
	v_ashrrev_i32_e32 v3, 31, v2
	v_lshlrev_b64 v[214:215], 12, v[2:3]
	v_pk_add_f32 v[28:29], v[12:13], v[26:27]
	v_sub_f32_e32 v13, v14, v213
	v_sub_f32_e32 v14, v30, v213
	v_pk_add_f32 v[28:29], v[28:29], v[28:29] op_sel_hi:[0,1]
	v_exp_f32_e32 v27, v14
	v_sub_f32_e32 v14, v15, v213
	v_exp_f32_e32 v13, v13
	v_exp_f32_e32 v28, v14
	v_sub_f32_e32 v14, v31, v213
	v_exp_f32_e32 v14, v14
	v_sub_f32_e32 v15, v16, v213
	v_exp_f32_e32 v63, v15
	v_sub_f32_e32 v15, v32, v213
	v_exp_f32_e32 v32, v15
	v_add_f32_e32 v15, v27, v13
	v_pk_add_f32 v[30:31], v[14:15], v[28:29]
	v_bitop3_b32 v2, v52, 15, v237 bitop3:0x48
	v_pk_add_f32 v[30:31], v[30:31], v[30:31] op_sel_hi:[0,1]
	v_sub_f32_e32 v15, v17, v213
	v_lshlrev_b32_e32 v2, 4, v2
	v_exp_f32_e32 v30, v15
	v_sub_f32_e32 v15, v33, v213
	v_or3_b32 v214, v214, s37, v2
	v_or_b32_e32 v2, s27, v53
	v_exp_f32_e32 v50, v15
	v_ashrrev_i32_e32 v3, 31, v2
	v_cvt_pk_bf16_f32 v179, v62, v4
	v_lshlrev_b64 v[2:3], 15, v[2:3]
	v_bitop3_b32 v4, v54, 7, v237 bitop3:0x48
	v_lshl_or_b32 v2, v4, 4, v2
	v_add_f32_e32 v51, v32, v63
	v_lshl_add_u64 v[216:217], v[2:3], 0, s[44:45]
	v_sub_u32_e32 v2, v236, v235
	v_mov_b64_e32 v[48:49], s[98:99]
	v_pk_add_f32 v[16:17], v[50:51], v[30:31]
	v_subrev_u32_e32 v2, s22, v2
	v_mov_b64_e32 v[36:37], s[86:87]
	v_mov_b64_e32 v[38:39], s[88:89]
	v_mov_b64_e32 v[40:41], s[90:91]
	v_mov_b64_e32 v[42:43], s[92:93]
	v_mov_b64_e32 v[44:45], s[94:95]
	v_mov_b64_e32 v[46:47], s[96:97]
	v_xor_b32_e32 v66, 0x80000000, v213
	v_add_f32_e32 v242, v16, v17
	v_cvt_pk_bf16_f32 v164, v5, v20
	v_cvt_pk_bf16_f32 v165, v7, v22
	v_cvt_pk_bf16_f32 v170, v9, v24
	v_cvt_pk_bf16_f32 v171, v11, v26
	v_cvt_pk_bf16_f32 v172, v13, v28
	v_cvt_pk_bf16_f32 v173, v63, v30
	v_cvt_pk_bf16_f32 v180, v19, v6
	v_cvt_pk_bf16_f32 v181, v21, v8
	v_cvt_pk_bf16_f32 v186, v23, v10
	v_cvt_pk_bf16_f32 v187, v25, v12
	v_cvt_pk_bf16_f32 v188, v27, v14
	v_cvt_pk_bf16_f32 v189, v32, v50
	v_subrev_u32_e32 v248, s21, v2
	v_mov_b64_e32 v[64:65], v[48:49]
	v_mov_b64_e32 v[18:19], v[34:35]
	v_mov_b64_e32 v[2:3], v[34:35]
	v_readlane_b32 s94, v255, 10
	v_readlane_b32 s90, v255, 12
	v_mov_b32_e32 v67, v66
	v_mov_b32_e32 v68, v66
	v_mov_b32_e32 v69, v66
	v_mov_b32_e32 v70, v66
	v_mov_b32_e32 v71, v66
	v_mov_b32_e32 v72, v66
	v_mov_b32_e32 v73, v66
	v_mov_b32_e32 v74, v66
	v_mov_b32_e32 v75, v66
	v_mov_b32_e32 v76, v66
	v_mov_b32_e32 v77, v66
	v_mov_b32_e32 v78, v66
	v_mov_b32_e32 v79, v66
	v_mov_b32_e32 v80, v66
	v_mov_b32_e32 v81, v66
	s_mov_b32 s21, 0
	v_mov_b32_e32 v166, 0
	v_mov_b32_e32 v167, 0
	v_mov_b32_e32 v168, 0
	v_mov_b32_e32 v169, 0
	v_mov_b32_e32 v174, 0
	v_mov_b32_e32 v175, 0
	v_mov_b32_e32 v176, 0
	v_mov_b32_e32 v177, 0
	v_mov_b32_e32 v182, 0
	v_mov_b32_e32 v183, 0
	v_mov_b32_e32 v184, 0
	v_mov_b32_e32 v185, 0
	v_mov_b32_e32 v190, 0
	v_mov_b32_e32 v191, 0
	v_mov_b32_e32 v192, 0
	v_mov_b32_e32 v193, 0
	v_mov_b64_e32 v[62:63], v[46:47]
	v_mov_b64_e32 v[60:61], v[44:45]
	v_mov_b64_e32 v[58:59], v[42:43]
	v_mov_b64_e32 v[56:57], v[40:41]
	v_mov_b64_e32 v[54:55], v[38:39]
	v_mov_b64_e32 v[52:53], v[36:37]
	v_mov_b64_e32 v[50:51], v[34:35]
	v_mov_b64_e32 v[20:21], v[36:37]
	v_mov_b64_e32 v[22:23], v[38:39]
	v_mov_b64_e32 v[24:25], v[40:41]
	v_mov_b64_e32 v[26:27], v[42:43]
	v_mov_b64_e32 v[28:29], v[44:45]
	v_mov_b64_e32 v[30:31], v[46:47]
	v_mov_b64_e32 v[32:33], v[48:49]
	v_mov_b64_e32 v[4:5], v[36:37]
	v_mov_b64_e32 v[6:7], v[38:39]
	v_mov_b64_e32 v[8:9], v[40:41]
	v_mov_b64_e32 v[10:11], v[42:43]
	v_mov_b64_e32 v[12:13], v[44:45]
	v_mov_b64_e32 v[14:15], v[46:47]
	v_mov_b64_e32 v[16:17], v[48:49]
	s_mov_b32 s33, 0x4000
	s_mov_b32 s48, 0
	s_mov_b32 s49, 0
	s_movk_i32 s92, 0x6e
	s_movk_i32 s93, 0xd0
	s_mov_b32 s57, 0x41000000
	v_readlane_b32 s95, v255, 11
	v_readlane_b32 s91, v255, 13
	s_add_u32 s80, s8, 0xd0c0000
	s_addc_u32 s81, s9, 0
	s_add_u32 s62, s8, 0xd0e0000
	s_addc_u32 s63, s9, 0
	s_add_u32 s96, s8, 0x15000100
	s_addc_u32 s97, s9, 0
	s_add_u32 s58, s8, 0x15200100
	s_addc_u32 s59, s9, 0
	s_add_u32 s50, s8, 0xd100000
	s_addc_u32 s51, s9, 0
	s_add_u32 s4, s8, 0xd120000
	s_addc_u32 s5, s9, 0
	s_add_u32 s0, s8, 0x15000180
	s_addc_u32 s1, s9, 0
	s_add_u32 s52, s8, 0x15200180
	s_addc_u32 s53, s9, 0
	v_add_u32_e32 v244, 0x8000, v244
	v_add_u32_e32 v245, 0x8000, v245
	v_add_u32_e32 v246, 0x8000, v246
	v_add_u32_e32 v247, 0x8000, v247
	ds_read_b128 v[202:205], v239 offset:16384
	ds_read_b128 v[194:197], v239 offset:24576
	ds_read_b128 v[198:201], v240 offset:16384
.LBB0_164:
	s_waitcnt vmcnt(2)
.LBB0_168:
	s_cmp_ge_u32 s23, s19
	s_cbranch_scc1 .Lslow_u1e
	s_barrier
.LBB0_174:
.LBB0_185:
	ds_read_b128 v[126:129], v244 offset:16384
	s_waitcnt lgkmcnt(1)
	v_mfma_f32_32x32x16_bf16 v[82:97], v[202:205], v[146:149], v[66:81]
	s_add_i32 s22, s23, -1
	s_cmp_lt_u32 s22, s16
	s_cselect_b64 s[88:89], -1, 0
	ds_read_b128 v[122:125], v240 offset:24576
	v_mfma_f32_32x32x16_bf16 v[98:113], v[194:197], v[146:149], v[66:81]
	ds_read_b128 v[114:117], v241 offset:16384
	v_mfma_f32_32x32x16_bf16 v[82:97], v[198:201], v[150:153], v[82:97]
	ds_read_b128 v[118:121], v241 offset:24576
	s_waitcnt lgkmcnt(0)
	v_mfma_f32_32x32x16_bf16 v[98:113], v[122:125], v[150:153], v[98:113]
	ds_read_b128 v[122:125], v243 offset:16384
	v_mfma_f32_32x32x16_bf16 v[82:97], v[114:117], v[154:157], v[82:97]
	ds_read_b128 v[114:117], v243 offset:24576
	v_mfma_f32_32x32x16_bf16 v[98:113], v[118:121], v[154:157], v[98:113]
	s_waitcnt lgkmcnt(0)
	v_mfma_f32_32x32x16_bf16 v[82:97], v[122:125], v[158:161], v[82:97]
	v_mfma_f32_32x32x16_bf16 v[98:113], v[114:117], v[158:161], v[98:113]
	s_nop 0
	ds_read_b128 v[122:125], v244 offset:20480
	ds_read_b128 v[118:121], v244 offset:24576
	ds_read_b128 v[114:117], v244 offset:28672
	s_add_i32 s22, s21, 64
	s_cmp_le_u32 s22, s20
	s_cbranch_scc0 .Lnear_u1e

.LBB0_208:
	s_add_i32 s40, s23, 1
	s_cmp_ge_u32 s40, s19
	s_cbranch_scc1 .Lslow_u1o
	s_barrier
.LBB0_214:
.LBB0_225:
	ds_read_b128 v[126:129], v244 offset:32768
	s_waitcnt lgkmcnt(1)
	v_mfma_f32_32x32x16_bf16 v[82:97], v[202:205], v[146:149], v[66:81]
	ds_read_b128 v[122:125], v240 offset:40960
	v_mfma_f32_32x32x16_bf16 v[98:113], v[194:197], v[146:149], v[66:81]
	ds_read_b128 v[114:117], v241 offset:32768
	v_mfma_f32_32x32x16_bf16 v[82:97], v[198:201], v[150:153], v[82:97]
	ds_read_b128 v[118:121], v241 offset:40960
	s_waitcnt lgkmcnt(0)
	v_mfma_f32_32x32x16_bf16 v[98:113], v[122:125], v[150:153], v[98:113]
	ds_read_b128 v[122:125], v243 offset:32768
	v_mfma_f32_32x32x16_bf16 v[82:97], v[114:117], v[154:157], v[82:97]
	ds_read_b128 v[114:117], v243 offset:40960
	v_mfma_f32_32x32x16_bf16 v[98:113], v[118:121], v[154:157], v[98:113]
	s_waitcnt lgkmcnt(0)
	v_mfma_f32_32x32x16_bf16 v[82:97], v[122:125], v[158:161], v[82:97]
	v_mfma_f32_32x32x16_bf16 v[98:113], v[114:117], v[158:161], v[98:113]
	s_nop 0
	ds_read_b128 v[122:125], v244 offset:36864
	ds_read_b128 v[118:121], v244 offset:40960
	ds_read_b128 v[114:117], v244 offset:45056
	s_add_i32 s26, s21, 0x80
	s_cmp_le_u32 s26, s20
	s_cbranch_scc0 .Lnear_u1o

.Lslow_u1e:
	s_barrier
	s_add_i32 s22, s23, -1
	s_cmp_lt_u32 s22, s16
	s_cselect_b64 s[88:89], -1, 0
	s_add_i32 s22, s23, -1
	s_cmp_lt_u32 s22, s19
	s_cbranch_scc1 .Lpvo_u1e
	s_branch .Lhd_u1e
.Lslow_u1o:
	s_barrier
	s_cmp_lt_u32 s23, s19
	s_cbranch_scc1 .Lpvo_u1o
	s_branch .Lhd_u1o

.Lotail_u1o:
	s_add_i32 s26, s23, -1
	s_cmp_lt_u32 s26, s16
	s_cbranch_scc1 .Low2_u1o
	s_waitcnt vmcnt(0)
	s_branch .LBB0_208
.Lr1u1_LBB0_164:
	s_waitcnt vmcnt(2)

.Lr1u1_LBB0_174:
.Lr1u1_LBB0_185:
	ds_read_b128 v[126:129], v244 offset:49152
	s_waitcnt lgkmcnt(1)
	v_mfma_f32_32x32x16_bf16 v[82:97], v[202:205], v[146:149], v[66:81]
	s_add_i32 s22, s23, -1
	s_cmp_lt_u32 s22, s16
	s_cselect_b64 s[88:89], -1, 0
	ds_read_b128 v[122:125], v240 offset:8192
	v_mfma_f32_32x32x16_bf16 v[98:113], v[194:197], v[146:149], v[66:81]
	ds_read_b128 v[114:117], v241
	v_mfma_f32_32x32x16_bf16 v[82:97], v[198:201], v[150:153], v[82:97]
	ds_read_b128 v[118:121], v241 offset:8192
	s_waitcnt lgkmcnt(0)
	v_mfma_f32_32x32x16_bf16 v[98:113], v[122:125], v[150:153], v[98:113]
	ds_read_b128 v[122:125], v243
	v_mfma_f32_32x32x16_bf16 v[82:97], v[114:117], v[154:157], v[82:97]
	ds_read_b128 v[114:117], v243 offset:8192
	v_mfma_f32_32x32x16_bf16 v[98:113], v[118:121], v[154:157], v[98:113]
	s_waitcnt lgkmcnt(0)
	v_mfma_f32_32x32x16_bf16 v[82:97], v[122:125], v[158:161], v[82:97]
	v_mfma_f32_32x32x16_bf16 v[98:113], v[114:117], v[158:161], v[98:113]
	s_nop 0
	ds_read_b128 v[122:125], v244 offset:53248
	ds_read_b128 v[118:121], v244 offset:57344
	ds_read_b128 v[114:117], v244 offset:61440
	s_add_i32 s22, s21, 64
	s_cmp_le_u32 s22, s20
	s_cbranch_scc0 .Lr1u1_Lnear_u1e

.Lr1u1_LBB0_214:
.Lr1u1_LBB0_225:
	ds_read_b128 v[126:129], v244 offset:16384
	s_waitcnt lgkmcnt(1)
	v_mfma_f32_32x32x16_bf16 v[82:97], v[202:205], v[146:149], v[66:81]
	ds_read_b128 v[122:125], v240 offset:24576
	v_mfma_f32_32x32x16_bf16 v[98:113], v[194:197], v[146:149], v[66:81]
	ds_read_b128 v[114:117], v241 offset:16384
	v_mfma_f32_32x32x16_bf16 v[82:97], v[198:201], v[150:153], v[82:97]
	ds_read_b128 v[118:121], v241 offset:24576
	s_waitcnt lgkmcnt(0)
	v_mfma_f32_32x32x16_bf16 v[98:113], v[122:125], v[150:153], v[98:113]
	ds_read_b128 v[122:125], v243 offset:16384
	v_mfma_f32_32x32x16_bf16 v[82:97], v[114:117], v[154:157], v[82:97]
	ds_read_b128 v[114:117], v243 offset:24576
	v_mfma_f32_32x32x16_bf16 v[98:113], v[118:121], v[154:157], v[98:113]
	s_waitcnt lgkmcnt(0)
	v_mfma_f32_32x32x16_bf16 v[82:97], v[122:125], v[158:161], v[82:97]
	v_mfma_f32_32x32x16_bf16 v[98:113], v[114:117], v[158:161], v[98:113]
	s_nop 0
	ds_read_b128 v[122:125], v244 offset:20480
	ds_read_b128 v[118:121], v244 offset:24576
	ds_read_b128 v[114:117], v244 offset:28672
	s_add_i32 s26, s21, 0x80
	s_cmp_le_u32 s26, s20
	s_cbranch_scc0 .Lr1u1_Lnear_u1o

.Lr1u1_Lotail_u1o:
	s_add_i32 s26, s23, -1
	s_cmp_lt_u32 s26, s16
	s_cbranch_scc1 .Lr1u1_Low2_u1o
	s_waitcnt vmcnt(0)
	s_branch .Lr1u1_LBB0_208
.Lr2u1_LBB0_164:
	s_waitcnt vmcnt(2)

.Lr2u1_LBB0_174:
.Lr2u1_LBB0_185:
	ds_read_b128 v[126:129], v244 offset:32768
	s_waitcnt lgkmcnt(1)
	v_mfma_f32_32x32x16_bf16 v[82:97], v[202:205], v[146:149], v[66:81]
	s_add_i32 s22, s23, -1
	s_cmp_lt_u32 s22, s16
	s_cselect_b64 s[88:89], -1, 0
	ds_read_b128 v[122:125], v240 offset:40960
	v_mfma_f32_32x32x16_bf16 v[98:113], v[194:197], v[146:149], v[66:81]
	ds_read_b128 v[114:117], v241 offset:32768
	v_mfma_f32_32x32x16_bf16 v[82:97], v[198:201], v[150:153], v[82:97]
	ds_read_b128 v[118:121], v241 offset:40960
	s_waitcnt lgkmcnt(0)
	v_mfma_f32_32x32x16_bf16 v[98:113], v[122:125], v[150:153], v[98:113]
	ds_read_b128 v[122:125], v243 offset:32768
	v_mfma_f32_32x32x16_bf16 v[82:97], v[114:117], v[154:157], v[82:97]
	ds_read_b128 v[114:117], v243 offset:40960
	v_mfma_f32_32x32x16_bf16 v[98:113], v[118:121], v[154:157], v[98:113]
	s_waitcnt lgkmcnt(0)
	v_mfma_f32_32x32x16_bf16 v[82:97], v[122:125], v[158:161], v[82:97]
	v_mfma_f32_32x32x16_bf16 v[98:113], v[114:117], v[158:161], v[98:113]
	s_nop 0
	ds_read_b128 v[122:125], v244 offset:36864
	ds_read_b128 v[118:121], v244 offset:40960
	ds_read_b128 v[114:117], v244 offset:45056
	s_add_i32 s22, s21, 64
	s_cmp_le_u32 s22, s20
	s_cbranch_scc0 .Lr2u1_Lnear_u1e

.Lr2u1_LBB0_214:
.Lr2u1_LBB0_225:
	ds_read_b128 v[126:129], v244 offset:49152
	s_waitcnt lgkmcnt(1)
	v_mfma_f32_32x32x16_bf16 v[82:97], v[202:205], v[146:149], v[66:81]
	ds_read_b128 v[122:125], v240 offset:8192
	v_mfma_f32_32x32x16_bf16 v[98:113], v[194:197], v[146:149], v[66:81]
	ds_read_b128 v[114:117], v241
	v_mfma_f32_32x32x16_bf16 v[82:97], v[198:201], v[150:153], v[82:97]
	ds_read_b128 v[118:121], v241 offset:8192
	s_waitcnt lgkmcnt(0)
	v_mfma_f32_32x32x16_bf16 v[98:113], v[122:125], v[150:153], v[98:113]
	ds_read_b128 v[122:125], v243
	v_mfma_f32_32x32x16_bf16 v[82:97], v[114:117], v[154:157], v[82:97]
	ds_read_b128 v[114:117], v243 offset:8192
	v_mfma_f32_32x32x16_bf16 v[98:113], v[118:121], v[154:157], v[98:113]
	s_waitcnt lgkmcnt(0)
	v_mfma_f32_32x32x16_bf16 v[82:97], v[122:125], v[158:161], v[82:97]
	v_mfma_f32_32x32x16_bf16 v[98:113], v[114:117], v[158:161], v[98:113]
	s_nop 0
	ds_read_b128 v[122:125], v244 offset:53248
	ds_read_b128 v[118:121], v244 offset:57344
	ds_read_b128 v[114:117], v244 offset:61440
	s_add_i32 s26, s21, 0x80
	s_cmp_le_u32 s26, s20
	s_cbranch_scc0 .Lr2u1_Lnear_u1o

.LBB0_266:
	s_nop 6
	v_max_f32_e32 v0, v19, v19
	v_max_f32_e32 v39, v3, v3
	v_max_f32_e32 v0, v39, v0
	v_max3_f32 v0, v2, v18, v0
	v_max3_f32 v39, v20, v5, v21
	v_max3_f32 v0, v0, v4, v39
	v_max3_f32 v39, v22, v7, v23
	v_max3_f32 v0, v0, v6, v39
	v_max3_f32 v39, v24, v9, v25
	v_max3_f32 v0, v0, v8, v39
	v_max3_f32 v39, v26, v11, v27
	v_max3_f32 v0, v0, v10, v39
	v_max3_f32 v39, v28, v13, v29
	v_max3_f32 v0, v0, v12, v39
	v_max3_f32 v39, v30, v15, v31
	v_max3_f32 v0, v0, v14, v39
	v_max3_f32 v39, v32, v17, v33
	v_max3_f32 v0, v0, v16, v39
	v_mov_b32_e32 v39, v0
	s_nop 1
	v_permlane32_swap_b32_e32 v0, v39
	v_max_f32_e32 v39, v39, v39
	v_max_f32_e32 v0, v0, v0
	v_max_f32_e32 v213, v0, v39
	v_sub_f32_e32 v0, v2, v213
	v_exp_f32_e32 v40, v0
	v_sub_f32_e32 v0, v18, v213
	v_exp_f32_e32 v41, v0
	v_sub_f32_e32 v0, v3, v213
	v_sub_f32_e32 v2, v19, v213
	v_exp_f32_e32 v0, v0
	v_exp_f32_e32 v2, v2
	v_add_f32_e32 v3, v41, v40
	s_movk_i32 s27, 0x510
	v_cvt_pk_bf16_f32 v162, v40, v0
	v_pk_add_f32 v[18:19], v[2:3], v[0:1]
	v_sub_f32_e32 v3, v4, v213
	v_sub_f32_e32 v4, v20, v213
	v_pk_add_f32 v[18:19], v[18:19], v[18:19] op_sel_hi:[0,1]
	v_exp_f32_e32 v43, v4
	v_sub_f32_e32 v4, v5, v213
	v_exp_f32_e32 v3, v3
	v_exp_f32_e32 v18, v4
	v_sub_f32_e32 v4, v21, v213
	v_exp_f32_e32 v4, v4
	v_add_f32_e32 v5, v43, v3
	v_xad_u32 v0, v37, -1, v236
	v_cvt_pk_bf16_f32 v178, v41, v2
	v_pk_add_f32 v[20:21], v[4:5], v[18:19]
	v_sub_f32_e32 v5, v6, v213
	v_sub_f32_e32 v6, v22, v213
	v_pk_add_f32 v[20:21], v[20:21], v[20:21] op_sel_hi:[0,1]
	v_exp_f32_e32 v19, v6
	v_sub_f32_e32 v6, v7, v213
	v_exp_f32_e32 v5, v5
	v_exp_f32_e32 v20, v6
	v_sub_f32_e32 v6, v23, v213
	v_exp_f32_e32 v6, v6
	v_add_f32_e32 v7, v19, v5
	v_and_b32_e32 v0, 3, v0
	v_mov_b32_e32 v2, s31
	v_pk_add_f32 v[22:23], v[6:7], v[20:21]
	v_sub_f32_e32 v7, v8, v213
	v_sub_f32_e32 v8, v24, v213
	v_pk_add_f32 v[22:23], v[22:23], v[22:23] op_sel_hi:[0,1]
	v_exp_f32_e32 v21, v8
	v_sub_f32_e32 v8, v9, v213
	v_exp_f32_e32 v7, v7
	v_exp_f32_e32 v22, v8
	v_sub_f32_e32 v8, v25, v213
	v_exp_f32_e32 v8, v8
	v_add_f32_e32 v9, v21, v7
	s_add_i32 s20, s20, s56
	v_mad_u32_u24 v244, v0, s27, v2
	v_pk_add_f32 v[24:25], v[8:9], v[22:23]
	v_sub_f32_e32 v9, v10, v213
	v_sub_f32_e32 v10, v26, v213
	v_pk_add_f32 v[24:25], v[24:25], v[24:25] op_sel_hi:[0,1]
	v_exp_f32_e32 v23, v10
	v_sub_f32_e32 v10, v11, v213
	v_exp_f32_e32 v9, v9
	v_exp_f32_e32 v24, v10
	v_sub_f32_e32 v10, v27, v213
	v_exp_f32_e32 v10, v10
	v_add_f32_e32 v11, v23, v9
	v_add_u32_e32 v2, s20, v233
	v_cvt_pk_bf16_f32 v163, v3, v18
	v_pk_add_f32 v[26:27], v[10:11], v[24:25]
	v_sub_f32_e32 v11, v12, v213
	v_sub_f32_e32 v12, v28, v213
	v_pk_add_f32 v[26:27], v[26:27], v[26:27] op_sel_hi:[0,1]
	v_exp_f32_e32 v25, v12
	v_sub_f32_e32 v12, v13, v213
	v_exp_f32_e32 v11, v11
	v_exp_f32_e32 v26, v12
	v_sub_f32_e32 v12, v29, v213
	v_exp_f32_e32 v12, v12
	v_add_f32_e32 v13, v25, v11
	v_ashrrev_i32_e32 v3, 31, v2
	v_lshlrev_b64 v[2:3], 12, v[2:3]
	v_pk_add_f32 v[28:29], v[12:13], v[26:27]
	v_sub_f32_e32 v13, v14, v213
	v_sub_f32_e32 v14, v30, v213
	v_pk_add_f32 v[28:29], v[28:29], v[28:29] op_sel_hi:[0,1]
	v_exp_f32_e32 v27, v14
	v_sub_f32_e32 v14, v15, v213
	v_exp_f32_e32 v13, v13
	v_exp_f32_e32 v28, v14
	v_sub_f32_e32 v14, v31, v213
	v_exp_f32_e32 v14, v14
	v_sub_f32_e32 v15, v16, v213
	v_exp_f32_e32 v48, v15
	v_sub_f32_e32 v15, v32, v213
	v_exp_f32_e32 v32, v15
	v_add_f32_e32 v15, v27, v13
	v_pk_add_f32 v[30:31], v[14:15], v[28:29]
	v_and_b32_e32 v0, 15, v34
	v_pk_add_f32 v[30:31], v[30:31], v[30:31] op_sel_hi:[0,1]
	v_sub_f32_e32 v15, v17, v213
	v_or_b32_e32 v2, s37, v2
	v_lshlrev_b32_e32 v0, 4, v0
	s_add_i32 s21, s21, s36
	v_exp_f32_e32 v30, v15
	v_sub_f32_e32 v15, v33, v213
	v_lshl_add_u64 v[214:215], v[2:3], 0, v[0:1]
	v_add_u32_e32 v2, s21, v36
	v_and_b32_e32 v39, 7, v38
	v_bitop3_b32 v44, v38, v234, 7 bitop3:0x6c
	v_exp_f32_e32 v38, v15
	v_ashrrev_i32_e32 v3, 31, v2
	v_lshlrev_b64 v[2:3], 15, v[2:3]
	v_and_b32_e32 v0, 7, v35
	s_and_b32 s26, s47, 15
	v_lshl_or_b32 v2, v0, 4, v2
	v_sub_u32_e32 v0, v236, v235
	v_lshlrev_b32_e32 v42, 7, v235
	v_bitop3_b32 v45, v234, v39, 2 bitop3:0x36
	v_bitop3_b32 v46, v234, v39, 4 bitop3:0x36
	v_bitop3_b32 v47, v234, v39, 6 bitop3:0x36
	s_lshl_b32 s26, s26, 7
	v_add_f32_e32 v39, v32, v48
	v_cvt_pk_bf16_f32 v188, v27, v14
	v_subrev_u32_e32 v0, s28, v0
	v_mov_b32_e32 v14, v1
	v_mov_b32_e32 v15, v1
	s_lshl_b32 s17, s46, 1
	s_lshr_b32 s19, s16, 6
	v_pk_add_f32 v[16:17], v[38:39], v[30:31]
	v_cvt_pk_bf16_f32 v164, v5, v20
	v_cvt_pk_bf16_f32 v165, v7, v22
	v_cvt_pk_bf16_f32 v170, v9, v24
	v_cvt_pk_bf16_f32 v171, v11, v26
	v_cvt_pk_bf16_f32 v172, v13, v28
	v_cvt_pk_bf16_f32 v173, v48, v30
	v_cvt_pk_bf16_f32 v179, v43, v4
	v_cvt_pk_bf16_f32 v180, v19, v6
	v_cvt_pk_bf16_f32 v181, v21, v8
	v_cvt_pk_bf16_f32 v186, v23, v10
	v_cvt_pk_bf16_f32 v187, v25, v12
	v_cvt_pk_bf16_f32 v189, v32, v38
	v_lshl_or_b32 v245, v44, 4, v42
	v_lshl_or_b32 v246, v45, 4, v42
	v_lshl_or_b32 v247, v46, 4, v42
	v_lshl_or_b32 v248, v47, 4, v42
	v_lshl_add_u64 v[216:217], v[2:3], 0, s[44:45]
	v_subrev_u32_e32 v249, s26, v0
	v_mov_b32_e32 v0, v1
	v_mov_b32_e32 v2, v1
	v_mov_b32_e32 v3, v1
	v_mov_b32_e32 v4, v1
	v_mov_b32_e32 v5, v1
	v_mov_b32_e32 v6, v1
	v_mov_b32_e32 v7, v1
	v_mov_b32_e32 v8, v1
	v_mov_b32_e32 v9, v1
	v_mov_b32_e32 v10, v1
	v_mov_b32_e32 v11, v1
	v_mov_b32_e32 v12, v1
	v_mov_b32_e32 v13, v1
	v_mov_b64_e32 v[64:65], v[14:15]
	v_mov_b64_e32 v[48:49], v[14:15]
	v_mov_b64_e32 v[32:33], v[14:15]
	s_add_i32 s18, s17, 2
	s_add_i32 s19, s19, 1
	v_xor_b32_e32 v66, 0x80000000, v213
	v_add_f32_e32 v243, v16, v17
	v_mov_b64_e32 v[62:63], v[12:13]
	v_mov_b64_e32 v[60:61], v[10:11]
	v_mov_b64_e32 v[58:59], v[8:9]
	v_mov_b64_e32 v[56:57], v[6:7]
	v_mov_b64_e32 v[54:55], v[4:5]
	v_mov_b64_e32 v[52:53], v[2:3]
	v_mov_b64_e32 v[50:51], v[0:1]
	v_mov_b64_e32 v[46:47], v[12:13]
	v_mov_b64_e32 v[44:45], v[10:11]
	v_mov_b64_e32 v[42:43], v[8:9]
	v_mov_b64_e32 v[40:41], v[6:7]
	v_mov_b64_e32 v[38:39], v[4:5]
	v_mov_b64_e32 v[36:37], v[2:3]
	v_mov_b64_e32 v[34:35], v[0:1]
	v_mov_b64_e32 v[30:31], v[12:13]
	v_mov_b64_e32 v[28:29], v[10:11]
	v_mov_b64_e32 v[26:27], v[8:9]
	v_mov_b64_e32 v[24:25], v[6:7]
	v_mov_b64_e32 v[22:23], v[4:5]
	v_mov_b64_e32 v[20:21], v[2:3]
	v_mov_b64_e32 v[18:19], v[0:1]
	v_mov_b64_e32 v[16:17], v[14:15]
	s_mov_b32 s22, 1
	s_mov_b32 s23, 0x8000
	s_min_u32 s19, s18, s19
	v_mov_b32_e32 v67, v66
	v_mov_b32_e32 v68, v66
	v_mov_b32_e32 v69, v66
	v_mov_b32_e32 v70, v66
	v_mov_b32_e32 v71, v66
	v_mov_b32_e32 v72, v66
	v_mov_b32_e32 v73, v66
	v_mov_b32_e32 v74, v66
	v_mov_b32_e32 v75, v66
	v_mov_b32_e32 v76, v66
	v_mov_b32_e32 v77, v66
	v_mov_b32_e32 v78, v66
	v_mov_b32_e32 v79, v66
	v_mov_b32_e32 v80, v66
	v_mov_b32_e32 v81, v66
	s_mov_b32 s28, 0
	s_movk_i32 s20, 0xf0
	v_mov_b32_e32 v166, 0
	v_mov_b32_e32 v167, 0
	v_mov_b32_e32 v168, 0
	v_mov_b32_e32 v169, 0
	v_mov_b32_e32 v174, 0
	v_mov_b32_e32 v175, 0
	v_mov_b32_e32 v176, 0
	v_mov_b32_e32 v177, 0
	v_mov_b32_e32 v182, 0
	v_mov_b32_e32 v183, 0
	v_mov_b32_e32 v184, 0
	v_mov_b32_e32 v185, 0
	v_mov_b32_e32 v190, 0
	v_mov_b32_e32 v191, 0
	v_mov_b32_e32 v192, 0
	v_mov_b32_e32 v193, 0
	v_mov_b64_e32 v[14:15], v[12:13]
	v_mov_b64_e32 v[12:13], v[10:11]
	v_mov_b64_e32 v[10:11], v[8:9]
	v_mov_b64_e32 v[8:9], v[6:7]
	v_mov_b64_e32 v[6:7], v[4:5]
	v_mov_b64_e32 v[4:5], v[2:3]
	v_mov_b64_e32 v[2:3], v[0:1]
	s_mov_b32 s31, 0x4000
	s_mov_b32 s33, 0
	v_add_u32_e32 v245, 0x8000, v245
	v_add_u32_e32 v246, 0x8000, v246
	v_add_u32_e32 v247, 0x8000, v247
	v_add_u32_e32 v248, 0x8000, v248
	ds_read_b128 v[202:205], v239 offset:16384
	ds_read_b128 v[194:197], v239 offset:24576
	ds_read_b128 v[198:201], v240 offset:16384
.LBB0_267:
	s_waitcnt vmcnt(2)
.LBB0_271:
	s_cmp_ge_u32 s22, s19
	s_cbranch_scc1 .Lslow_u2e
	s_barrier
.LBB0_277:
.LBB0_288:
	ds_read_b128 v[126:129], v245 offset:16384
	s_waitcnt lgkmcnt(1)
	v_mfma_f32_32x32x16_bf16 v[82:97], v[202:205], v[146:149], v[66:81]
	s_add_i32 s21, s22, -1
	s_cmp_lt_u32 s21, s17
	s_cselect_b64 s[44:45], -1, 0
	ds_read_b128 v[122:125], v240 offset:24576
	v_mfma_f32_32x32x16_bf16 v[98:113], v[194:197], v[146:149], v[66:81]
	ds_read_b128 v[114:117], v241 offset:16384
	v_mfma_f32_32x32x16_bf16 v[82:97], v[198:201], v[150:153], v[82:97]
	ds_read_b128 v[118:121], v241 offset:24576
	s_waitcnt lgkmcnt(0)
	v_mfma_f32_32x32x16_bf16 v[98:113], v[122:125], v[150:153], v[98:113]
	ds_read_b128 v[122:125], v242 offset:16384
	v_mfma_f32_32x32x16_bf16 v[82:97], v[114:117], v[154:157], v[82:97]
	ds_read_b128 v[114:117], v242 offset:24576
	v_mfma_f32_32x32x16_bf16 v[98:113], v[118:121], v[154:157], v[98:113]
	s_waitcnt lgkmcnt(0)
	v_mfma_f32_32x32x16_bf16 v[82:97], v[122:125], v[158:161], v[82:97]
	v_mfma_f32_32x32x16_bf16 v[98:113], v[114:117], v[158:161], v[98:113]
	s_nop 0
	ds_read_b128 v[122:125], v245 offset:20480
	ds_read_b128 v[118:121], v245 offset:24576
	ds_read_b128 v[114:117], v245 offset:28672
	s_cmp_le_u32 s20, s16
	s_cbranch_scc0 .Lnear_u2e

.LBB0_311:
	s_add_i32 s37, s22, 1
	s_cmp_ge_u32 s37, s19
	s_cbranch_scc1 .Lslow_u2o
	s_barrier
.LBB0_317:
.LBB0_328:
	ds_read_b128 v[126:129], v245 offset:32768
	s_waitcnt lgkmcnt(1)
	v_mfma_f32_32x32x16_bf16 v[82:97], v[202:205], v[146:149], v[66:81]
	ds_read_b128 v[122:125], v240 offset:40960
	v_mfma_f32_32x32x16_bf16 v[98:113], v[194:197], v[146:149], v[66:81]
	ds_read_b128 v[114:117], v241 offset:32768
	v_mfma_f32_32x32x16_bf16 v[82:97], v[198:201], v[150:153], v[82:97]
	ds_read_b128 v[118:121], v241 offset:40960
	s_waitcnt lgkmcnt(0)
	v_mfma_f32_32x32x16_bf16 v[98:113], v[122:125], v[150:153], v[98:113]
	ds_read_b128 v[122:125], v242 offset:32768
	v_mfma_f32_32x32x16_bf16 v[82:97], v[114:117], v[154:157], v[82:97]
	ds_read_b128 v[114:117], v242 offset:40960
	v_mfma_f32_32x32x16_bf16 v[98:113], v[118:121], v[154:157], v[98:113]
	s_waitcnt lgkmcnt(0)
	v_mfma_f32_32x32x16_bf16 v[82:97], v[122:125], v[158:161], v[82:97]
	v_mfma_f32_32x32x16_bf16 v[98:113], v[114:117], v[158:161], v[98:113]
	s_nop 0
	ds_read_b128 v[122:125], v245 offset:36864
	ds_read_b128 v[118:121], v245 offset:40960
	ds_read_b128 v[114:117], v245 offset:45056
	s_add_i32 s26, s20, 64
	s_cmp_le_u32 s26, s16
	s_cbranch_scc0 .Lnear_u2o

.Lslow_u2e:
	s_barrier
	s_add_i32 s21, s22, -1
	s_cmp_lt_u32 s21, s17
	s_cselect_b64 s[44:45], -1, 0
	s_add_i32 s21, s22, -1
	s_cmp_lt_u32 s21, s19
	s_cbranch_scc1 .Lpvo_u2e
	s_branch .Lhd_u2e
.Lslow_u2o:
	s_barrier
	s_cmp_lt_u32 s22, s19
	s_cbranch_scc1 .Lpvo_u2o
	s_branch .Lhd_u2o

.Lotail_u2o:
	s_add_i32 s26, s22, -1
	s_cmp_lt_u32 s26, s17
	s_cbranch_scc1 .Low2_u2o
	s_waitcnt vmcnt(0)
	s_branch .LBB0_311
.Lr1u2_LBB0_267:
	s_waitcnt vmcnt(2)

.Lr1u2_LBB0_277:
.Lr1u2_LBB0_288:
	ds_read_b128 v[126:129], v245 offset:49152
	s_waitcnt lgkmcnt(1)
	v_mfma_f32_32x32x16_bf16 v[82:97], v[202:205], v[146:149], v[66:81]
	s_add_i32 s21, s22, -1
	s_cmp_lt_u32 s21, s17
	s_cselect_b64 s[44:45], -1, 0
	ds_read_b128 v[122:125], v240 offset:8192
	v_mfma_f32_32x32x16_bf16 v[98:113], v[194:197], v[146:149], v[66:81]
	ds_read_b128 v[114:117], v241
	v_mfma_f32_32x32x16_bf16 v[82:97], v[198:201], v[150:153], v[82:97]
	ds_read_b128 v[118:121], v241 offset:8192
	s_waitcnt lgkmcnt(0)
	v_mfma_f32_32x32x16_bf16 v[98:113], v[122:125], v[150:153], v[98:113]
	ds_read_b128 v[122:125], v242
	v_mfma_f32_32x32x16_bf16 v[82:97], v[114:117], v[154:157], v[82:97]
	ds_read_b128 v[114:117], v242 offset:8192
	v_mfma_f32_32x32x16_bf16 v[98:113], v[118:121], v[154:157], v[98:113]
	s_waitcnt lgkmcnt(0)
	v_mfma_f32_32x32x16_bf16 v[82:97], v[122:125], v[158:161], v[82:97]
	v_mfma_f32_32x32x16_bf16 v[98:113], v[114:117], v[158:161], v[98:113]
	s_nop 0
	ds_read_b128 v[122:125], v245 offset:53248
	ds_read_b128 v[118:121], v245 offset:57344
	ds_read_b128 v[114:117], v245 offset:61440
	s_cmp_le_u32 s20, s16
	s_cbranch_scc0 .Lr1u2_Lnear_u2e

.Lr1u2_LBB0_317:
.Lr1u2_LBB0_328:
	ds_read_b128 v[126:129], v245 offset:16384
	s_waitcnt lgkmcnt(1)
	v_mfma_f32_32x32x16_bf16 v[82:97], v[202:205], v[146:149], v[66:81]
	ds_read_b128 v[122:125], v240 offset:24576
	v_mfma_f32_32x32x16_bf16 v[98:113], v[194:197], v[146:149], v[66:81]
	ds_read_b128 v[114:117], v241 offset:16384
	v_mfma_f32_32x32x16_bf16 v[82:97], v[198:201], v[150:153], v[82:97]
	ds_read_b128 v[118:121], v241 offset:24576
	s_waitcnt lgkmcnt(0)
	v_mfma_f32_32x32x16_bf16 v[98:113], v[122:125], v[150:153], v[98:113]
	ds_read_b128 v[122:125], v242 offset:16384
	v_mfma_f32_32x32x16_bf16 v[82:97], v[114:117], v[154:157], v[82:97]
	ds_read_b128 v[114:117], v242 offset:24576
	v_mfma_f32_32x32x16_bf16 v[98:113], v[118:121], v[154:157], v[98:113]
	s_waitcnt lgkmcnt(0)
	v_mfma_f32_32x32x16_bf16 v[82:97], v[122:125], v[158:161], v[82:97]
	v_mfma_f32_32x32x16_bf16 v[98:113], v[114:117], v[158:161], v[98:113]
	s_nop 0
	ds_read_b128 v[122:125], v245 offset:20480
	ds_read_b128 v[118:121], v245 offset:24576
	ds_read_b128 v[114:117], v245 offset:28672
	s_add_i32 s26, s20, 64
	s_cmp_le_u32 s26, s16
	s_cbranch_scc0 .Lr1u2_Lnear_u2o

.Lr1u2_Lotail_u2o:
	s_add_i32 s26, s22, -1
	s_cmp_lt_u32 s26, s17
	s_cbranch_scc1 .Lr1u2_Low2_u2o
	s_waitcnt vmcnt(0)
	s_branch .Lr1u2_LBB0_311
.Lr2u2_LBB0_267:
	s_waitcnt vmcnt(2)

.Lr2u2_LBB0_277:
.Lr2u2_LBB0_288:
	ds_read_b128 v[126:129], v245 offset:32768
	s_waitcnt lgkmcnt(1)
	v_mfma_f32_32x32x16_bf16 v[82:97], v[202:205], v[146:149], v[66:81]
	s_add_i32 s21, s22, -1
	s_cmp_lt_u32 s21, s17
	s_cselect_b64 s[44:45], -1, 0
	ds_read_b128 v[122:125], v240 offset:40960
	v_mfma_f32_32x32x16_bf16 v[98:113], v[194:197], v[146:149], v[66:81]
	ds_read_b128 v[114:117], v241 offset:32768
	v_mfma_f32_32x32x16_bf16 v[82:97], v[198:201], v[150:153], v[82:97]
	ds_read_b128 v[118:121], v241 offset:40960
	s_waitcnt lgkmcnt(0)
	v_mfma_f32_32x32x16_bf16 v[98:113], v[122:125], v[150:153], v[98:113]
	ds_read_b128 v[122:125], v242 offset:32768
	v_mfma_f32_32x32x16_bf16 v[82:97], v[114:117], v[154:157], v[82:97]
	ds_read_b128 v[114:117], v242 offset:40960
	v_mfma_f32_32x32x16_bf16 v[98:113], v[118:121], v[154:157], v[98:113]
	s_waitcnt lgkmcnt(0)
	v_mfma_f32_32x32x16_bf16 v[82:97], v[122:125], v[158:161], v[82:97]
	v_mfma_f32_32x32x16_bf16 v[98:113], v[114:117], v[158:161], v[98:113]
	s_nop 0
	ds_read_b128 v[122:125], v245 offset:36864
	ds_read_b128 v[118:121], v245 offset:40960
	ds_read_b128 v[114:117], v245 offset:45056
	s_cmp_le_u32 s20, s16
	s_cbranch_scc0 .Lr2u2_Lnear_u2e

.Lr2u2_LBB0_317:
.Lr2u2_LBB0_328:
	ds_read_b128 v[126:129], v245 offset:49152
	s_waitcnt lgkmcnt(1)
	v_mfma_f32_32x32x16_bf16 v[82:97], v[202:205], v[146:149], v[66:81]
	ds_read_b128 v[122:125], v240 offset:8192
	v_mfma_f32_32x32x16_bf16 v[98:113], v[194:197], v[146:149], v[66:81]
	ds_read_b128 v[114:117], v241
	v_mfma_f32_32x32x16_bf16 v[82:97], v[198:201], v[150:153], v[82:97]
	ds_read_b128 v[118:121], v241 offset:8192
	s_waitcnt lgkmcnt(0)
	v_mfma_f32_32x32x16_bf16 v[98:113], v[122:125], v[150:153], v[98:113]
	ds_read_b128 v[122:125], v242
	v_mfma_f32_32x32x16_bf16 v[82:97], v[114:117], v[154:157], v[82:97]
	ds_read_b128 v[114:117], v242 offset:8192
	v_mfma_f32_32x32x16_bf16 v[98:113], v[118:121], v[154:157], v[98:113]
	s_waitcnt lgkmcnt(0)
	v_mfma_f32_32x32x16_bf16 v[82:97], v[122:125], v[158:161], v[82:97]
	v_mfma_f32_32x32x16_bf16 v[98:113], v[114:117], v[158:161], v[98:113]
	s_nop 0
	ds_read_b128 v[122:125], v245 offset:53248
	ds_read_b128 v[118:121], v245 offset:57344
	ds_read_b128 v[114:117], v245 offset:61440
	s_add_i32 s26, s20, 64
	s_cmp_le_u32 s26, s16
	s_cbranch_scc0 .Lr2u2_Lnear_u2o
